# delta prep pass A: V-group address math and loads hoisted to the top of the iteration beside the K-group loads (renamed registers)
# speedup vs baseline: 1.0013x; 1.0013x over previous
; #define LAS __attribute__((address_space(3)))
; __device__ __forceinline__ float silu_f(float x) { return x * sigmoid_f(x); }
; __device__ __forceinline__ void conv8h(const bf16* p, const bf16* halo, int nloc, const LAS float* w, float* a) {
; #pragma unroll
;     for (int e = 0; e < 8; ++e) a[e] = 0.f;
; #pragma unroll
;     for (int j = 0; j < 4; ++j) {
;         const int r = nloc - 3 + j;
;         const u32x4 u = *(const u32x4*)(r >= 0 ? p - (ptrdiff_t)(3 - j) * D : halo + (r + 3) * D);
;         const f32x4 w0 = *(const LAS f32x4*)(w + j * 128), w1 = *(const LAS f32x4*)(w + j * 128 + 4);
;         a[0] += bflo(u.x) * w0[0]; a[1] += bfhi(u.x) * w0[1]; a[2] += bflo(u.y) * w0[2]; a[3] += bfhi(u.y) * w0[3];
;         a[4] += bflo(u.z) * w1[0]; a[5] += bfhi(u.z) * w1[1]; a[6] += bflo(u.w) * w1[2]; a[7] += bfhi(u.w) * w1[3];
;     }
; #pragma unroll
;     for (int e = 0; e < 8; ++e) a[e] = silu_f(a[e]);
; }
.LBB0_1038:
	s_or_b64 exec, exec, s[4:5]
	s_waitcnt vmcnt(6)
	v_lshlrev_b32_e32 v160, 16, v200
	v_and_b32_e32 v161, 0xffff0000, v200
	v_lshlrev_b32_e32 v48, 16, v201
	v_and_b32_e32 v49, 0xffff0000, v201
	s_waitcnt lgkmcnt(14)
	v_pk_fma_f32 v[92:93], v[92:93], v[160:161], 0 op_sel_hi:[1,1,0]
	s_waitcnt vmcnt(4)
	v_lshlrev_b32_e32 v160, 16, v208
	v_and_b32_e32 v161, 0xffff0000, v208
	v_pk_fma_f32 v[48:49], v[94:95], v[48:49], 0 op_sel_hi:[1,1,0]
	v_lshlrev_b32_e32 v52, 16, v209
	v_and_b32_e32 v53, 0xffff0000, v209
	s_waitcnt lgkmcnt(13)
	v_pk_fma_f32 v[48:49], v[90:91], v[52:53], v[48:49]
	s_waitcnt vmcnt(2)
	v_lshlrev_b32_e32 v52, 16, v217
	v_and_b32_e32 v53, 0xffff0000, v217
	s_waitcnt lgkmcnt(11)
	v_pk_fma_f32 v[48:49], v[86:87], v[52:53], v[48:49]
	s_waitcnt vmcnt(0)
	v_lshlrev_b32_e32 v52, 16, v225
	v_and_b32_e32 v53, 0xffff0000, v225
	s_waitcnt lgkmcnt(9)
	v_pk_fma_f32 v[48:49], v[82:83], v[52:53], v[48:49]
	v_lshlrev_b32_e32 v52, 16, v202
	v_and_b32_e32 v53, 0xffff0000, v202
	v_lshlrev_b32_e32 v50, 16, v203
	v_and_b32_e32 v51, 0xffff0000, v203
	v_pk_fma_f32 v[88:89], v[88:89], v[160:161], v[92:93]
	v_lshlrev_b32_e32 v92, 16, v216
	v_and_b32_e32 v93, 0xffff0000, v216
	v_pk_fma_f32 v[52:53], v[76:77], v[52:53], 0 op_sel_hi:[1,1,0]
	v_lshlrev_b32_e32 v56, 16, v210
	v_and_b32_e32 v57, 0xffff0000, v210
	v_pk_fma_f32 v[50:51], v[78:79], v[50:51], 0 op_sel_hi:[1,1,0]
	v_lshlrev_b32_e32 v54, 16, v211
	v_and_b32_e32 v55, 0xffff0000, v211
	v_pk_fma_f32 v[52:53], v[72:73], v[56:57], v[52:53]
	v_lshlrev_b32_e32 v56, 16, v218
	v_and_b32_e32 v57, 0xffff0000, v218
	v_pk_fma_f32 v[50:51], v[74:75], v[54:55], v[50:51]
	v_lshlrev_b32_e32 v54, 16, v219
	v_and_b32_e32 v55, 0xffff0000, v219
	v_pk_fma_f32 v[52:53], v[68:69], v[56:57], v[52:53]
	v_lshlrev_b32_e32 v56, 16, v226
	v_and_b32_e32 v57, 0xffff0000, v226
	v_pk_fma_f32 v[50:51], v[70:71], v[54:55], v[50:51]
	v_lshlrev_b32_e32 v54, 16, v227
	v_and_b32_e32 v55, 0xffff0000, v227
	v_lshlrev_b32_e32 v62, 16, v196
	v_and_b32_e32 v63, 0xffff0000, v196
	v_lshlrev_b32_e32 v0, 16, v197
	v_and_b32_e32 v1, 0xffff0000, v197
	s_waitcnt lgkmcnt(7)
	v_pk_fma_f32 v[44:45], v[44:45], v[62:63], 0 op_sel_hi:[1,1,0]
	v_lshlrev_b32_e32 v62, 16, v204
	v_and_b32_e32 v63, 0xffff0000, v204
	v_pk_fma_f32 v[0:1], v[46:47], v[0:1], 0 op_sel_hi:[1,1,0]
	v_lshlrev_b32_e32 v4, 16, v205
	v_and_b32_e32 v5, 0xffff0000, v205
	s_waitcnt lgkmcnt(5)
	v_pk_fma_f32 v[0:1], v[42:43], v[4:5], v[0:1]
	v_lshlrev_b32_e32 v4, 16, v213
	v_and_b32_e32 v5, 0xffff0000, v213
	s_waitcnt lgkmcnt(3)
	v_pk_fma_f32 v[0:1], v[38:39], v[4:5], v[0:1]
	v_lshlrev_b32_e32 v4, 16, v221
	v_and_b32_e32 v5, 0xffff0000, v221
	s_waitcnt lgkmcnt(1)
	v_pk_fma_f32 v[0:1], v[34:35], v[4:5], v[0:1]
	v_lshlrev_b32_e32 v4, 16, v198
	v_and_b32_e32 v5, 0xffff0000, v198
	v_pk_fma_f32 v[40:41], v[40:41], v[62:63], v[44:45]
	v_lshlrev_b32_e32 v44, 16, v212
	v_and_b32_e32 v45, 0xffff0000, v212
	v_pk_fma_f32 v[4:5], v[28:29], v[4:5], 0 op_sel_hi:[1,1,0]
	v_lshlrev_b32_e32 v8, 16, v206
	v_and_b32_e32 v9, 0xffff0000, v206
	v_pk_fma_f32 v[36:37], v[36:37], v[44:45], v[40:41]
	v_lshlrev_b32_e32 v40, 16, v220
	v_and_b32_e32 v41, 0xffff0000, v220
	v_pk_fma_f32 v[4:5], v[24:25], v[8:9], v[4:5]
	v_lshlrev_b32_e32 v8, 16, v214
	v_and_b32_e32 v9, 0xffff0000, v214
	v_pk_fma_f32 v[32:33], v[32:33], v[40:41], v[36:37]
	v_pk_fma_f32 v[4:5], v[20:21], v[8:9], v[4:5]
	v_lshlrev_b32_e32 v8, 16, v222
	v_and_b32_e32 v9, 0xffff0000, v222
	s_waitcnt lgkmcnt(0)
	v_pk_fma_f32 v[4:5], v[16:17], v[8:9], v[4:5]
	v_lshlrev_b32_e32 v2, 16, v199
	v_and_b32_e32 v3, 0xffff0000, v199
	v_mul_f32_e32 v8, 0xbfb8aa3b, v32
	v_mul_f32_e32 v9, 0xbfb8aa3b, v33
	v_pk_fma_f32 v[2:3], v[30:31], v[2:3], 0 op_sel_hi:[1,1,0]
	v_lshlrev_b32_e32 v6, 16, v207
	v_and_b32_e32 v7, 0xffff0000, v207
	v_exp_f32_e32 v8, v8
	v_exp_f32_e32 v9, v9
	v_pk_fma_f32 v[2:3], v[26:27], v[6:7], v[2:3]
	v_lshlrev_b32_e32 v6, 16, v215
	v_and_b32_e32 v7, 0xffff0000, v215
	v_pk_fma_f32 v[84:85], v[84:85], v[92:93], v[88:89]
	v_lshlrev_b32_e32 v88, 16, v224
	v_and_b32_e32 v89, 0xffff0000, v224
	v_pk_fma_f32 v[2:3], v[22:23], v[6:7], v[2:3]
	v_lshlrev_b32_e32 v6, 16, v223
	v_and_b32_e32 v7, 0xffff0000, v223
	v_pk_fma_f32 v[80:81], v[80:81], v[88:89], v[84:85]
	v_pk_fma_f32 v[2:3], v[18:19], v[6:7], v[2:3]
	v_pk_fma_f32 v[52:53], v[64:65], v[56:57], v[52:53]
	v_mul_f32_e32 v56, 0xbfb8aa3b, v80
	v_mul_f32_e32 v57, 0xbfb8aa3b, v81
	v_add_f32_e32 v6, 1.0, v8
	v_add_f32_e32 v7, 1.0, v9
	v_mul_f32_e32 v8, 0xbfb8aa3b, v0
	v_mul_f32_e32 v9, 0xbfb8aa3b, v1
	v_mul_f32_e32 v10, 0xbfb8aa3b, v4
	v_mul_f32_e32 v11, 0xbfb8aa3b, v5
	v_mul_f32_e32 v12, 0xbfb8aa3b, v2
	v_mul_f32_e32 v13, 0xbfb8aa3b, v3
	v_exp_f32_e32 v56, v56
	v_exp_f32_e32 v57, v57
	v_exp_f32_e32 v8, v8
	v_exp_f32_e32 v9, v9
	v_exp_f32_e32 v10, v10
	v_exp_f32_e32 v11, v11
	v_exp_f32_e32 v12, v12
	v_exp_f32_e32 v13, v13
	v_pk_fma_f32 v[50:51], v[66:67], v[54:55], v[50:51]
	v_add_f32_e32 v54, 1.0, v56
	v_add_f32_e32 v55, 1.0, v57
	v_mul_f32_e32 v56, 0xbfb8aa3b, v48
	v_mul_f32_e32 v57, 0xbfb8aa3b, v49
	v_mul_f32_e32 v58, 0xbfb8aa3b, v52
	v_mul_f32_e32 v59, 0xbfb8aa3b, v53
	v_mul_f32_e32 v60, 0xbfb8aa3b, v50
	v_mul_f32_e32 v61, 0xbfb8aa3b, v51
	v_add_f32_e32 v8, 1.0, v8
	v_add_f32_e32 v9, 1.0, v9
	v_add_f32_e32 v10, 1.0, v10
	v_add_f32_e32 v11, 1.0, v11
	v_add_f32_e32 v12, 1.0, v12
	v_add_f32_e32 v13, 1.0, v13
	v_exp_f32_e32 v56, v56
	v_exp_f32_e32 v57, v57
	v_exp_f32_e32 v58, v58
	v_exp_f32_e32 v59, v59
	v_exp_f32_e32 v60, v60
	v_exp_f32_e32 v61, v61
	v_rcp_f32_e32 v8, v8
	v_rcp_f32_e32 v9, v9
	v_rcp_f32_e32 v10, v10
	v_rcp_f32_e32 v11, v11
	v_rcp_f32_e32 v12, v12
	v_rcp_f32_e32 v13, v13
; __device__ __forceinline__ float rsq_f(float x) { return __builtin_amdgcn_rsqf(x); }
; __device__ __forceinline__ float red8(float x) { x += dpp_f<0xB1>(x); x += dpp_f<0x4E>(x); x += dpp_f<0x141>(x); return x; }
; __device__ __forceinline__ float* karg_out() { return *(volatile KAS fptr_t*)((const KAS char*)__builtin_amdgcn_kernarg_segment_ptr() + 256); }
; #define lane opq(lane_now())
; __device__ __forceinline__ void delta_prep_wave(const Params& P, LAS unsigned char* lds, int idx, int wave, int lane) {
;     ...
;         const int nloc = it * 8 + (lane >> 3), tl = span * 64 + nloc, d0 = (lane & 7) * 16; const size_t ro = ((size_t)b * SEQ + tl) * D + h * 128 + d0;
;         float kv[16], qv[16], vv[16];
;         conv8h(Kb + ro, HK + d0, nloc, wk + d0, kv); conv8h(Kb + ro + 8, HK + d0 + 8, nloc, wk + d0 + 8, kv + 8);
;         conv8(Qb + ro, tl, wq + d0, qv); conv8(Qb + ro + 8, tl, wq + d0 + 8, qv + 8);
;         conv8h(Vb + ro, HV + d0, nloc, wv + d0, vv); conv8h(Vb + ro + 8, HV + d0 + 8, nloc, wv + d0 + 8, vv + 8);
;         float ssk = 0.f, ssq = 0.f;
; #pragma unroll
;         for (int e = 0; e < 16; ++e) { ssk += kv[e] * kv[e]; ssq += qv[e] * qv[e]; }
;         ssk = red8(ssk); ssq = red8(ssq);
;         if ((lane & 7) == 0) { const float nkj = rsq_f(ssk + EPS), nqj = 0.08838834764831845f * rsq_f(ssq + EPS); nks[nloc] = nkj; nqs[nloc] = nqj;
;             ((float*)((unsigned char*)karg_out() + OSB_NK))[(size_t)bh * SEQ + tl] = nkj; ((float*)((unsigned char*)karg_out() + OSB_NQ))[(size_t)bh * SEQ + tl] = nqj; }
;         *(bf16x8*)(Kb + ro) = pack8(kv[0], kv[1], kv[2], kv[3], kv[4], kv[5], kv[6], kv[7]); *(bf16x8*)(Kb + ro + 8) = pack8(kv[8], kv[9], kv[10], kv[11], kv[12], kv[13], kv[14], kv[15]);
;         *(bf16x8*)(QT + ro) = pack8(qv[0], qv[1], qv[2], qv[3], qv[4], qv[5], qv[6], qv[7]); *(bf16x8*)(QT + ro + 8) = pack8(qv[8], qv[9], qv[10], qv[11], qv[12], qv[13], qv[14], qv[15]);
;         *(bf16x8*)(Vb + ro) = pack8(vv[0], vv[1], vv[2], vv[3], vv[4], vv[5], vv[6], vv[7]); *(bf16x8*)(Vb + ro + 8) = pack8(vv[8], vv[9], vv[10], vv[11], vv[12], vv[13], vv[14], vv[15]);
	v_add_f32_e32 v56, 1.0, v56
	v_add_f32_e32 v57, 1.0, v57
	v_add_f32_e32 v58, 1.0, v58
	v_add_f32_e32 v59, 1.0, v59
	v_add_f32_e32 v60, 1.0, v60
	v_add_f32_e32 v61, 1.0, v61
	v_pk_mul_f32 v[8:9], v[0:1], v[8:9]
	v_pk_mul_f32 v[4:5], v[4:5], v[10:11]
	v_pk_mul_f32 v[10:11], v[2:3], v[12:13]
	v_cvt_pk_bf16_f32 v0, v116, v117
	v_cvt_pk_bf16_f32 v1, v118, v119
	v_cvt_pk_bf16_f32 v2, v120, v121
	v_cvt_pk_bf16_f32 v3, v122, v123
	v_add_co_u32_e32 v12, vcc, s60, v112
	v_rcp_f32_e32 v54, v54
	v_rcp_f32_e32 v55, v55
	v_rcp_f32_e32 v56, v56
	v_rcp_f32_e32 v57, v57
	v_rcp_f32_e32 v58, v58
	v_rcp_f32_e32 v59, v59
	v_rcp_f32_e32 v60, v60
	v_rcp_f32_e32 v61, v61
	global_store_dwordx4 v[114:115], v[0:3], off
	v_addc_co_u32_e32 v13, vcc, 0, v113, vcc
	s_nop 0
	v_cvt_pk_bf16_f32 v0, v124, v125
	v_cvt_pk_bf16_f32 v1, v126, v127
	v_cvt_pk_bf16_f32 v2, v128, v129
	v_cvt_pk_bf16_f32 v3, v130, v131
	global_store_dwordx4 v[12:13], v[0:3], off offset:16
	v_lshl_add_u64 v[12:13], v[110:111], 0, s[38:39]
	v_rcp_f32_e32 v6, v6
	v_rcp_f32_e32 v7, v7
	v_add_co_u32_e32 v12, vcc, s61, v12
	v_cvt_pk_bf16_f32 v0, v132, v133
	v_cvt_pk_bf16_f32 v1, v134, v135
	v_cvt_pk_bf16_f32 v2, v136, v137
	v_cvt_pk_bf16_f32 v3, v138, v139
	v_addc_co_u32_e32 v13, vcc, 0, v13, vcc
	v_pk_mul_f32 v[14:15], v[80:81], v[54:55]
	v_pk_mul_f32 v[16:17], v[48:49], v[56:57]
	v_pk_mul_f32 v[18:19], v[52:53], v[58:59]
	v_pk_mul_f32 v[20:21], v[50:51], v[60:61]
	global_store_dwordx4 v[12:13], v[0:3], off
	s_addk_i32 s35, 0xe000
	s_add_u32 s38, s38, 0xffffc000
	v_cvt_pk_bf16_f32 v0, v144, v145
	v_cvt_pk_bf16_f32 v1, v146, v147
	v_cvt_pk_bf16_f32 v2, v148, v149
	v_cvt_pk_bf16_f32 v3, v150, v151
	global_store_dwordx4 v[12:13], v[0:3], off offset:16
	v_pk_mul_f32 v[6:7], v[32:33], v[6:7]
	s_addc_u32 s39, s39, -1
	v_cvt_pk_bf16_f32 v0, v14, v15
	v_cvt_pk_bf16_f32 v1, v16, v17
	v_cvt_pk_bf16_f32 v2, v18, v19
	v_cvt_pk_bf16_f32 v3, v20, v21
	global_store_dwordx4 v[142:143], v[0:3], off
	v_subrev_u32_e32 v154, 32, v154
	v_add_u32_e32 v97, -8, v97
	v_cvt_pk_bf16_f32 v2, v4, v5
	v_add_co_u32_e32 v4, vcc, s62, v140
	v_cvt_pk_bf16_f32 v0, v6, v7
	v_cvt_pk_bf16_f32 v1, v8, v9
	v_cvt_pk_bf16_f32 v3, v10, v11
	v_addc_co_u32_e32 v5, vcc, 0, v141, vcc
	s_cmp_eq_u32 s35, 0xffff0000
	v_lshl_add_u64 v[102:103], v[102:103], 0, s[56:57]
	global_store_dwordx4 v[4:5], v[0:3], off offset:16
	s_cbranch_scc1 .LBB0_1041
.LBB0_1039:
	v_add_u32_e32 v8, s35, v155
	v_add_u32_e32 v6, 0xe800, v8
	v_ashrrev_i32_e32 v7, 31, v6
	v_lshl_add_u64 v[112:113], v[104:105], 0, s[38:39]
	v_lshlrev_b64 v[22:23], 1, v[6:7]
	v_lshl_add_u64 v[4:5], v[112:113], 0, s[44:45]
	v_lshl_add_u64 v[6:7], v[98:99], 0, v[22:23]
	v_cmp_lt_i32_e64 s[12:13], 0, v97
	v_add_u32_e32 v2, 0xe000, v8
	s_mov_b64 s[4:5], 0xb100000
	v_cndmask_b32_e64 v4, v6, v4, s[12:13]
	v_add_u32_e32 v6, 0xec00, v8
	v_ashrrev_i32_e32 v3, 31, v2
	v_cndmask_b32_e64 v5, v7, v5, s[12:13]
	v_ashrrev_i32_e32 v7, 31, v6
	v_lshl_add_u64 v[114:115], v[112:113], 0, s[4:5]
	s_mov_b64 s[4:5], 0xb0fe800
	v_lshlrev_b64 v[20:21], 1, v[2:3]
	v_lshlrev_b64 v[24:25], 1, v[6:7]
	v_lshl_add_u64 v[0:1], v[112:113], 0, s[4:5]
	v_lshl_add_u64 v[2:3], v[98:99], 0, v[20:21]
	v_cmp_lt_i32_e32 vcc, 2, v97
	v_lshl_add_u64 v[6:7], v[98:99], 0, v[24:25]
	v_cmp_gt_i32_e64 s[14:15], 0, v97
	v_cndmask_b32_e32 v1, v3, v1, vcc
	v_cndmask_b32_e32 v0, v2, v0, vcc
	v_cndmask_b32_e64 v9, v115, v7, s[14:15]
	v_cndmask_b32_e64 v8, v114, v6, s[14:15]
	v_lshl_add_u64 v[6:7], v[112:113], 0, s[40:41]
	v_lshl_add_u64 v[2:3], v[2:3], 0, s[42:43]
	v_cmp_lt_i32_e64 s[16:17], 1, v97
	global_load_dwordx4 v[16:19], v[0:1], off
	global_load_dwordx4 v[26:29], v[4:5], off
	v_cndmask_b32_e64 v11, v3, v7, s[16:17]
	v_cndmask_b32_e64 v10, v2, v6, s[16:17]
	global_load_dwordx4 v[34:37], v[10:11], off
	global_load_dwordx4 v[30:33], v[8:9], off
	ds_read_b128 v[38:41], v153 offset:2048
	ds_read_b128 v[42:45], v153 offset:2064
	ds_read_b128 v[46:49], v153 offset:2560
	ds_read_b128 v[50:53], v153 offset:2576
	ds_read_b128 v[54:57], v153 offset:3072
	ds_read_b128 v[58:61], v153 offset:3088
	ds_read_b128 v[62:65], v153 offset:3584
	ds_read_b128 v[66:69], v153 offset:3600
	global_load_dwordx4 v[12:15], v[0:1], off offset:16
	s_nop 0
	global_load_dwordx4 v[4:7], v[4:5], off offset:16
	s_nop 0
	global_load_dwordx4 v[0:3], v[8:9], off offset:16
	s_nop 0
	global_load_dwordx4 v[8:11], v[10:11], off offset:16
	v_add_u32_e32 v82, s34, v97
	v_cmp_lt_i32_e64 s[18:19], 2, v82
	v_lshl_add_u64 v[140:141], v[108:109], 0, s[38:39]
	v_lshl_add_u64 v[142:143], v[140:141], 0, s[48:49]
	v_lshl_add_u64 v[194:195], v[100:101], 0, v[20:21]
	v_lshl_add_u64 v[228:229], v[140:141], 0, s[50:51]
	v_cndmask_b32_e32 v231, v195, v229, vcc
	v_cndmask_b32_e32 v230, v194, v228, vcc
	global_load_dwordx4 v[196:199], v[230:231], off offset:16
	global_load_dwordx4 v[200:203], v[230:231], off
	v_lshl_add_u64 v[232:233], v[140:141], 0, s[52:53]
	v_lshl_add_u64 v[234:235], v[194:195], 0, s[42:43]
	v_cndmask_b32_e64 v237, v235, v233, s[16:17]
	v_cndmask_b32_e64 v236, v234, v232, s[16:17]
	global_load_dwordx4 v[204:207], v[236:237], off offset:16
	global_load_dwordx4 v[208:211], v[236:237], off
	v_lshl_add_u64 v[240:241], v[140:141], 0, s[54:55]
	v_lshl_add_u64 v[242:243], v[100:101], 0, v[22:23]
	v_cndmask_b32_e64 v245, v243, v241, s[12:13]
	v_cndmask_b32_e64 v244, v242, v240, s[12:13]
	global_load_dwordx4 v[212:215], v[244:245], off offset:16
	global_load_dwordx4 v[216:219], v[244:245], off
	v_lshl_add_u64 v[246:247], v[100:101], 0, v[24:25]
	v_cndmask_b32_e64 v249, v143, v247, s[14:15]
	v_cndmask_b32_e64 v248, v142, v246, s[14:15]
	global_load_dwordx4 v[220:223], v[248:249], off offset:16
	global_load_dwordx4 v[224:227], v[248:249], off
	s_waitcnt vmcnt(15)
; #define LAS __attribute__((address_space(3)))
; __device__ __forceinline__ float silu_f(float x) { return x * sigmoid_f(x); }
; __device__ __forceinline__ void conv8h(const bf16* p, const bf16* halo, int nloc, const LAS float* w, float* a) {
; #pragma unroll
;     for (int e = 0; e < 8; ++e) a[e] = 0.f;
; #pragma unroll
;     for (int j = 0; j < 4; ++j) {
;         const int r = nloc - 3 + j;
;         const u32x4 u = *(const u32x4*)(r >= 0 ? p - (ptrdiff_t)(3 - j) * D : halo + (r + 3) * D);
;         const f32x4 w0 = *(const LAS f32x4*)(w + j * 128), w1 = *(const LAS f32x4*)(w + j * 128 + 4);
;         a[0] += bflo(u.x) * w0[0]; a[1] += bfhi(u.x) * w0[1]; a[2] += bflo(u.y) * w0[2]; a[3] += bfhi(u.y) * w0[3];
;         a[4] += bflo(u.z) * w1[0]; a[5] += bfhi(u.z) * w1[1]; a[6] += bflo(u.w) * w1[2]; a[7] += bfhi(u.w) * w1[3];
;     }
; #pragma unroll
;     for (int e = 0; e < 8; ++e) a[e] = silu_f(a[e]);
; }
; __device__ __forceinline__ void delta_prep_wave(const Params& P, LAS unsigned char* lds, int idx, int wave, int lane) {
;     ...
;         conv8h(Kb + ro, HK + d0, nloc, wk + d0, kv); conv8h(Kb + ro + 8, HK + d0 + 8, nloc, wk + d0 + 8, kv + 8);
	v_lshlrev_b32_e32 v70, 16, v16
	v_and_b32_e32 v71, 0xffff0000, v16
	v_lshlrev_b32_e32 v16, 16, v17
	v_and_b32_e32 v17, 0xffff0000, v17
	v_lshlrev_b32_e32 v76, 16, v18
	v_and_b32_e32 v77, 0xffff0000, v18
	s_waitcnt lgkmcnt(7)
	v_pk_fma_f32 v[38:39], v[38:39], v[70:71], 0 op_sel_hi:[1,1,0]
	s_waitcnt vmcnt(13)
	v_lshlrev_b32_e32 v70, 16, v34
	v_and_b32_e32 v71, 0xffff0000, v34
	v_lshlrev_b32_e32 v72, 16, v26
	v_and_b32_e32 v73, 0xffff0000, v26
	v_pk_fma_f32 v[16:17], v[40:41], v[16:17], 0 op_sel_hi:[1,1,0]
	v_lshlrev_b32_e32 v34, 16, v35
	v_and_b32_e32 v35, 0xffff0000, v35
	s_waitcnt lgkmcnt(6)
	v_pk_fma_f32 v[40:41], v[42:43], v[76:77], 0 op_sel_hi:[1,1,0]
	v_lshlrev_b32_e32 v42, 16, v36
	v_and_b32_e32 v43, 0xffff0000, v36
	s_waitcnt lgkmcnt(5)
	v_pk_fma_f32 v[38:39], v[46:47], v[70:71], v[38:39]
	s_waitcnt vmcnt(12)
	v_lshlrev_b32_e32 v74, 16, v30
	v_and_b32_e32 v75, 0xffff0000, v30
	v_lshlrev_b32_e32 v26, 16, v27
	v_and_b32_e32 v27, 0xffff0000, v27
	v_lshlrev_b32_e32 v78, 16, v28
	v_and_b32_e32 v79, 0xffff0000, v28
	v_pk_fma_f32 v[16:17], v[48:49], v[34:35], v[16:17]
	s_waitcnt lgkmcnt(4)
	v_pk_fma_f32 v[34:35], v[50:51], v[42:43], v[40:41]
	s_waitcnt lgkmcnt(3)
	v_pk_fma_f32 v[38:39], v[54:55], v[72:73], v[38:39]
	v_lshlrev_b32_e32 v30, 16, v31
	v_and_b32_e32 v31, 0xffff0000, v31
	v_pk_fma_f32 v[16:17], v[56:57], v[26:27], v[16:17]
	s_waitcnt lgkmcnt(2)
	v_pk_fma_f32 v[26:27], v[58:59], v[78:79], v[34:35]
	s_waitcnt lgkmcnt(1)
	v_pk_fma_f32 v[34:35], v[62:63], v[74:75], v[38:39]
	v_pk_fma_f32 v[16:17], v[64:65], v[30:31], v[16:17]
	v_mul_f32_e32 v18, 0xbfb8aa3b, v34
	v_mul_f32_e32 v30, 0xbfb8aa3b, v16
	v_mul_f32_e32 v31, 0xbfb8aa3b, v17
	v_exp_f32_e32 v18, v18
	v_mul_f32_e32 v28, 0xbfb8aa3b, v35
	v_exp_f32_e32 v30, v30
	v_exp_f32_e32 v36, v31
	v_exp_f32_e32 v28, v28
	v_lshlrev_b32_e32 v80, 16, v32
	v_and_b32_e32 v81, 0xffff0000, v32
	s_waitcnt lgkmcnt(0)
	v_pk_fma_f32 v[26:27], v[66:67], v[80:81], v[26:27]
	v_add_f32_e32 v18, 1.0, v18
	v_mul_f32_e32 v32, 0xbfb8aa3b, v26
	v_add_f32_e32 v38, 1.0, v30
	v_rcp_f32_e32 v30, v18
	v_add_f32_e32 v18, 1.0, v36
	v_add_f32_e32 v28, 1.0, v28
	v_rcp_f32_e32 v38, v38
	v_rcp_f32_e32 v39, v18
	v_exp_f32_e32 v18, v32
	v_rcp_f32_e32 v31, v28
	v_mul_f32_e32 v28, 0xbfb8aa3b, v27
	v_exp_f32_e32 v28, v28
	v_pk_mul_f32 v[118:119], v[16:17], v[38:39]
	v_add_f32_e32 v16, 1.0, v18
	v_lshlrev_b32_e32 v18, 16, v19
	v_and_b32_e32 v19, 0xffff0000, v19
	v_pk_mul_f32 v[116:117], v[34:35], v[30:31]
	v_pk_fma_f32 v[18:19], v[44:45], v[18:19], 0 op_sel_hi:[1,1,0]
	v_lshlrev_b32_e32 v30, 16, v37
	v_and_b32_e32 v31, 0xffff0000, v37
	v_add_f32_e32 v17, 1.0, v28
	v_pk_fma_f32 v[18:19], v[52:53], v[30:31], v[18:19]
	v_lshlrev_b32_e32 v28, 16, v29
	v_and_b32_e32 v29, 0xffff0000, v29
	v_pk_fma_f32 v[18:19], v[60:61], v[28:29], v[18:19]
	v_lshlrev_b32_e32 v28, 16, v33
	v_and_b32_e32 v29, 0xffff0000, v33
	v_pk_fma_f32 v[54:55], v[68:69], v[28:29], v[18:19]
	v_rcp_f32_e32 v16, v16
	v_mul_f32_e32 v18, 0xbfb8aa3b, v54
	v_rcp_f32_e32 v17, v17
	v_exp_f32_e32 v18, v18
	v_mul_f32_e32 v19, 0xbfb8aa3b, v55
	v_exp_f32_e32 v19, v19
	v_pk_mul_f32 v[120:121], v[26:27], v[16:17]
	v_add_f32_e32 v16, 1.0, v18
	v_rcp_f32_e32 v56, v16
	v_add_f32_e32 v16, 1.0, v19
	v_rcp_f32_e32 v57, v16
	ds_read_b128 v[16:19], v153 offset:2080
	ds_read_b128 v[26:29], v153 offset:2096
	ds_read_b128 v[30:33], v153 offset:2592
	ds_read_b128 v[34:37], v153 offset:2608
	ds_read_b128 v[38:41], v153 offset:3104
	ds_read_b128 v[42:45], v153 offset:3120
	ds_read_b128 v[46:49], v153 offset:3616
	ds_read_b128 v[50:53], v153 offset:3632
	s_waitcnt vmcnt(11)
	v_lshlrev_b32_e32 v58, 16, v12
	v_and_b32_e32 v59, 0xffff0000, v12
	s_waitcnt lgkmcnt(7)
	v_pk_fma_f32 v[16:17], v[16:17], v[58:59], 0 op_sel_hi:[1,1,0]
	s_waitcnt vmcnt(8)
	v_lshlrev_b32_e32 v58, 16, v8
	v_and_b32_e32 v59, 0xffff0000, v8
	s_waitcnt lgkmcnt(5)
	v_pk_fma_f32 v[16:17], v[30:31], v[58:59], v[16:17]
	v_lshlrev_b32_e32 v30, 16, v4
	v_and_b32_e32 v31, 0xffff0000, v4
	s_waitcnt lgkmcnt(3)
	v_pk_fma_f32 v[16:17], v[38:39], v[30:31], v[16:17]
	v_lshlrev_b32_e32 v30, 16, v0
	v_and_b32_e32 v31, 0xffff0000, v0
	s_waitcnt lgkmcnt(1)
	v_pk_fma_f32 v[46:47], v[46:47], v[30:31], v[16:17]
	v_lshlrev_b32_e32 v12, 16, v13
	v_mul_f32_e32 v4, 0xbfb8aa3b, v47
	v_exp_f32_e32 v4, v4
	v_and_b32_e32 v13, 0xffff0000, v13
	v_pk_fma_f32 v[12:13], v[18:19], v[12:13], 0 op_sel_hi:[1,1,0]
	v_lshlrev_b32_e32 v8, 16, v9
	v_and_b32_e32 v9, 0xffff0000, v9
	v_add_f32_e32 v16, 1.0, v4
	v_pk_fma_f32 v[8:9], v[32:33], v[8:9], v[12:13]
	v_lshlrev_b32_e32 v4, 16, v5
	v_and_b32_e32 v5, 0xffff0000, v5
	v_pk_fma_f32 v[4:5], v[40:41], v[4:5], v[8:9]
	v_lshlrev_b32_e32 v8, 16, v1
	v_and_b32_e32 v9, 0xffff0000, v1
	v_pk_fma_f32 v[4:5], v[48:49], v[8:9], v[4:5]
	v_lshlrev_b32_e32 v12, 16, v14
	v_mul_f32_e32 v1, 0xbfb8aa3b, v4
	v_exp_f32_e32 v8, v1
	v_mul_f32_e32 v1, 0xbfb8aa3b, v5
	v_and_b32_e32 v13, 0xffff0000, v14
	v_exp_f32_e32 v9, v1
	v_rcp_f32_e32 v1, v16
	v_pk_fma_f32 v[12:13], v[26:27], v[12:13], 0 op_sel_hi:[1,1,0]
	v_lshlrev_b32_e32 v16, 16, v10
	v_and_b32_e32 v17, 0xffff0000, v10
	v_pk_fma_f32 v[12:13], v[34:35], v[16:17], v[12:13]
	v_lshlrev_b32_e32 v16, 16, v6
	v_and_b32_e32 v17, 0xffff0000, v6
	v_pk_fma_f32 v[12:13], v[42:43], v[16:17], v[12:13]
	v_lshlrev_b32_e32 v16, 16, v2
	v_and_b32_e32 v17, 0xffff0000, v2
	s_waitcnt lgkmcnt(0)
; #define LAS __attribute__((address_space(3)))
; __device__ __forceinline__ float silu_f(float x) { return x * sigmoid_f(x); }
; __device__ __forceinline__ void conv8(const bf16* p, int tl, const LAS float* w, float* a) {
; #pragma unroll
;     for (int e = 0; e < 8; ++e) a[e] = 0.f;
; #pragma unroll
;     for (int j = 0; j < 4; ++j) {
;         const bool ok = tl - 3 + j >= 0;
;         const u32x4 u = *(const u32x4*)(ok ? p - (ptrdiff_t)(3 - j) * D : p);
;         f32x4 w0 = *(const LAS f32x4*)(w + j * 128), w1 = *(const LAS f32x4*)(w + j * 128 + 4);
;         if (!ok) { w0 = (f32x4){0.f, 0.f, 0.f, 0.f}; w1 = w0; }
;         a[0] += bflo(u.x) * w0[0]; a[1] += bfhi(u.x) * w0[1]; a[2] += bflo(u.y) * w0[2]; a[3] += bfhi(u.y) * w0[3];
;         a[4] += bflo(u.z) * w1[0]; a[5] += bfhi(u.z) * w1[1]; a[6] += bflo(u.w) * w1[2]; a[7] += bfhi(u.w) * w1[3];
;     }
; #pragma unroll
;     for (int e = 0; e < 8; ++e) a[e] = silu_f(a[e]);
; }
	v_pk_fma_f32 v[12:13], v[50:51], v[16:17], v[12:13]
	v_cndmask_b32_e64 v17, 0, -1, s[18:19]
	v_cndmask_b32_e64 v16, 0, v156, s[18:19]
	v_lshl_add_u64 v[16:17], s[38:39], 0, v[16:17]
	v_lshl_add_u64 v[42:43], v[106:107], 0, v[16:17]
	v_add_co_u32_e64 v16, s[20:21], s59, v42
	v_lshlrev_b32_e32 v14, 16, v15
	s_nop 0
	v_addc_co_u32_e64 v17, s[20:21], 0, v43, s[20:21]
	v_cmp_lt_i32_e64 s[20:21], 1, v82
	v_and_b32_e32 v15, 0xffff0000, v15
	v_lshl_add_u64 v[34:35], v[106:107], 0, s[38:39]
	v_cndmask_b32_e64 v27, 0, -1, s[20:21]
	v_cndmask_b32_e64 v26, 0, v157, s[20:21]
	v_lshl_add_u64 v[26:27], s[38:39], 0, v[26:27]
	v_lshl_add_u64 v[48:49], v[106:107], 0, v[26:27]
	v_add_co_u32_e64 v26, s[22:23], s59, v48
	global_load_dwordx4 v[16:19], v[16:17], off
	s_nop 0
	v_addc_co_u32_e64 v27, s[22:23], 0, v49, s[22:23]
	v_cmp_lt_i32_e64 s[22:23], 0, v82
	v_pk_fma_f32 v[14:15], v[28:29], v[14:15], 0 op_sel_hi:[1,1,0]
	global_load_dwordx4 v[26:29], v[26:27], off
	v_cndmask_b32_e64 v31, 0, -1, s[22:23]
	v_cndmask_b32_e64 v30, 0, v158, s[22:23]
	v_lshl_add_u64 v[30:31], s[38:39], 0, v[30:31]
	v_lshl_add_u64 v[50:51], v[106:107], 0, v[30:31]
	v_add_co_u32_e64 v30, s[24:25], s59, v50
	v_mul_f32_e32 v6, 0xbfb8aa3b, v13
	s_nop 0
	v_addc_co_u32_e64 v31, s[24:25], 0, v51, s[24:25]
	v_add_co_u32_e64 v38, s[24:25], s59, v34
	global_load_dwordx4 v[30:33], v[30:31], off
	s_nop 0
	v_addc_co_u32_e64 v39, s[24:25], 0, v35, s[24:25]
	global_load_dwordx4 v[38:41], v[38:39], off
	v_exp_f32_e32 v6, v6
	v_lshlrev_b32_e32 v10, 16, v11
	v_and_b32_e32 v11, 0xffff0000, v11
	v_pk_mul_f32 v[122:123], v[54:55], v[56:57]
	v_add_f32_e32 v54, 1.0, v6
	v_pk_fma_f32 v[10:11], v[36:37], v[10:11], v[14:15]
	v_lshlrev_b32_e32 v6, 16, v7
	v_and_b32_e32 v7, 0xffff0000, v7
	v_pk_fma_f32 v[6:7], v[44:45], v[6:7], v[10:11]
	v_lshlrev_b32_e32 v10, 16, v3
	v_and_b32_e32 v11, 0xffff0000, v3
	v_pk_fma_f32 v[6:7], v[52:53], v[10:11], v[6:7]
	v_mul_f32_e32 v0, 0xbfb8aa3b, v46
	v_mul_f32_e32 v3, 0xbfb8aa3b, v6
	v_mul_f32_e32 v2, 0xbfb8aa3b, v12
	v_exp_f32_e32 v10, v3
	v_mul_f32_e32 v3, 0xbfb8aa3b, v7
	v_exp_f32_e32 v0, v0
	v_exp_f32_e32 v2, v2
	v_exp_f32_e32 v11, v3
	v_add_f32_e32 v8, 1.0, v8
	v_add_f32_e32 v0, 1.0, v0
	v_add_f32_e32 v9, 1.0, v9
	v_add_f32_e32 v2, 1.0, v2
	v_add_f32_e32 v10, 1.0, v10
	v_add_f32_e32 v11, 1.0, v11
	v_rcp_f32_e32 v0, v0
	v_rcp_f32_e32 v8, v8
	v_rcp_f32_e32 v9, v9
	v_rcp_f32_e32 v2, v2
	v_rcp_f32_e32 v3, v54
	v_rcp_f32_e32 v10, v10
	v_rcp_f32_e32 v11, v11
	v_pk_mul_f32 v[124:125], v[46:47], v[0:1]
	v_pk_mul_f32 v[126:127], v[4:5], v[8:9]
	v_pk_mul_f32 v[128:129], v[12:13], v[2:3]
	v_pk_mul_f32 v[130:131], v[6:7], v[10:11]
	v_lshl_add_u64 v[52:53], v[34:35], 0, s[46:47]
	ds_read_b128 v[0:3], v153
	v_lshl_add_u64 v[54:55], v[42:43], 0, s[46:47]
	ds_read_b128 v[4:7], v153 offset:16
	ds_read_b128 v[34:37], v153 offset:32
	ds_read_b128 v[42:45], v153 offset:48
	ds_read_b128 v[10:13], v153 offset:528
	v_cmp_lt_i32_e64 s[24:25], -1, v82
	s_waitcnt lgkmcnt(3)
	v_cndmask_b32_e64 v61, 0, v7, s[18:19]
	v_cndmask_b32_e64 v60, 0, v6, s[18:19]
	ds_read_b128 v[6:9], v153 offset:512
	s_waitcnt lgkmcnt(1)
	v_cndmask_b32_e64 v69, 0, v13, s[20:21]
	v_cndmask_b32_e64 v68, 0, v12, s[20:21]
	v_cndmask_b32_e64 v71, 0, v11, s[20:21]
	ds_read_b128 v[12:15], v153 offset:1024
	s_waitcnt lgkmcnt(1)
	v_cndmask_b32_e64 v65, 0, v9, s[20:21]
	v_cndmask_b32_e64 v64, 0, v8, s[20:21]
	v_cndmask_b32_e64 v70, 0, v10, s[20:21]
	ds_read_b128 v[8:11], v153 offset:1040
	v_cndmask_b32_e64 v59, 0, v1, s[18:19]
	v_cndmask_b32_e64 v58, 0, v0, s[18:19]
	v_cndmask_b32_e64 v63, 0, v5, s[18:19]
	v_cndmask_b32_e64 v62, 0, v4, s[18:19]
	v_lshl_add_u64 v[0:1], v[48:49], 0, s[46:47]
	v_lshl_add_u64 v[4:5], v[50:51], 0, s[46:47]
	v_cndmask_b32_e64 v57, 0, v3, s[18:19]
	v_cndmask_b32_e64 v56, 0, v2, s[18:19]
	global_load_dwordx4 v[0:3], v[0:1], off offset:16
	v_cndmask_b32_e64 v67, 0, v7, s[20:21]
	v_cndmask_b32_e64 v66, 0, v6, s[20:21]
	global_load_dwordx4 v[4:7], v[4:5], off offset:16
	s_waitcnt lgkmcnt(1)
	v_cndmask_b32_e64 v73, 0, v15, s[22:23]
	v_cndmask_b32_e64 v72, 0, v14, s[22:23]
	v_cndmask_b32_e64 v75, 0, v13, s[22:23]
	v_cndmask_b32_e64 v74, 0, v12, s[22:23]
	s_waitcnt lgkmcnt(0)
	v_cndmask_b32_e64 v77, 0, v11, s[22:23]
	v_cndmask_b32_e64 v76, 0, v10, s[22:23]
	v_cndmask_b32_e64 v79, 0, v9, s[22:23]
	v_cndmask_b32_e64 v78, 0, v8, s[22:23]
	ds_read_b128 v[46:49], v153 offset:1536
	global_load_dwordx4 v[12:15], v[54:55], off offset:16
	global_load_dwordx4 v[8:11], v[52:53], off offset:16
	s_waitcnt vmcnt(7)
	v_lshlrev_b32_e32 v54, 16, v16
	v_and_b32_e32 v55, 0xffff0000, v16
	v_pk_fma_f32 v[54:55], v[58:59], v[54:55], 0 op_sel_hi:[1,1,0]
	s_waitcnt vmcnt(6)
	v_lshlrev_b32_e32 v58, 16, v26
	v_and_b32_e32 v59, 0xffff0000, v26
	v_pk_fma_f32 v[54:55], v[66:67], v[58:59], v[54:55]
	s_waitcnt vmcnt(5)
	v_lshlrev_b32_e32 v58, 16, v30
	v_and_b32_e32 v59, 0xffff0000, v30
	s_waitcnt lgkmcnt(0)
	v_cndmask_b32_e64 v47, 0, v47, s[24:25]
	v_cndmask_b32_e64 v46, 0, v46, s[24:25]
	v_pk_fma_f32 v[54:55], v[74:75], v[58:59], v[54:55]
	s_waitcnt vmcnt(4)
; #define LAS __attribute__((address_space(3)))
; __device__ __forceinline__ float silu_f(float x) { return x * sigmoid_f(x); }
; __device__ __forceinline__ void conv8(const bf16* p, int tl, const LAS float* w, float* a) {
; #pragma unroll
;     for (int e = 0; e < 8; ++e) a[e] = 0.f;
; #pragma unroll
;     for (int j = 0; j < 4; ++j) {
;         const bool ok = tl - 3 + j >= 0;
;         const u32x4 u = *(const u32x4*)(ok ? p - (ptrdiff_t)(3 - j) * D : p);
;         f32x4 w0 = *(const LAS f32x4*)(w + j * 128), w1 = *(const LAS f32x4*)(w + j * 128 + 4);
;         if (!ok) { w0 = (f32x4){0.f, 0.f, 0.f, 0.f}; w1 = w0; }
;         a[0] += bflo(u.x) * w0[0]; a[1] += bfhi(u.x) * w0[1]; a[2] += bflo(u.y) * w0[2]; a[3] += bfhi(u.y) * w0[3];
;         a[4] += bflo(u.z) * w1[0]; a[5] += bfhi(u.z) * w1[1]; a[6] += bflo(u.w) * w1[2]; a[7] += bfhi(u.w) * w1[3];
;     }
; #pragma unroll
;     for (int e = 0; e < 8; ++e) a[e] = silu_f(a[e]);
; }
	v_lshlrev_b32_e32 v58, 16, v38
	v_and_b32_e32 v59, 0xffff0000, v38
	v_pk_fma_f32 v[46:47], v[46:47], v[58:59], v[54:55]
	v_lshlrev_b32_e32 v54, 16, v17
	v_mul_f32_e32 v26, 0xbfb8aa3b, v47
	v_exp_f32_e32 v26, v26
	v_and_b32_e32 v55, 0xffff0000, v17
	v_pk_fma_f32 v[54:55], v[56:57], v[54:55], 0 op_sel_hi:[1,1,0]
	v_lshlrev_b32_e32 v30, 16, v31
	v_add_f32_e32 v38, 1.0, v26
	v_lshlrev_b32_e32 v26, 16, v27
	v_and_b32_e32 v27, 0xffff0000, v27
	v_pk_fma_f32 v[26:27], v[64:65], v[26:27], v[54:55]
	v_and_b32_e32 v31, 0xffff0000, v31
	v_cndmask_b32_e64 v49, 0, v49, s[24:25]
	v_cndmask_b32_e64 v48, 0, v48, s[24:25]
	v_pk_fma_f32 v[26:27], v[72:73], v[30:31], v[26:27]
	v_lshlrev_b32_e32 v30, 16, v39
	v_and_b32_e32 v31, 0xffff0000, v39
	v_pk_fma_f32 v[26:27], v[48:49], v[30:31], v[26:27]
	ds_read_b128 v[50:53], v153 offset:1552
	v_mul_f32_e32 v17, 0xbfb8aa3b, v26
	v_exp_f32_e32 v30, v17
	v_mul_f32_e32 v17, 0xbfb8aa3b, v27
	v_exp_f32_e32 v31, v17
	v_rcp_f32_e32 v17, v38
	v_lshlrev_b32_e32 v38, 16, v18
	v_and_b32_e32 v39, 0xffff0000, v18
	v_pk_fma_f32 v[38:39], v[62:63], v[38:39], 0 op_sel_hi:[1,1,0]
	v_lshlrev_b32_e32 v48, 16, v28
	v_and_b32_e32 v49, 0xffff0000, v28
	v_pk_fma_f32 v[38:39], v[70:71], v[48:49], v[38:39]
	v_lshlrev_b32_e32 v48, 16, v32
	v_and_b32_e32 v49, 0xffff0000, v32
	s_waitcnt lgkmcnt(0)
	v_cndmask_b32_e64 v51, 0, v51, s[24:25]
	v_cndmask_b32_e64 v50, 0, v50, s[24:25]
	v_pk_fma_f32 v[38:39], v[78:79], v[48:49], v[38:39]
	v_lshlrev_b32_e32 v48, 16, v40
	v_and_b32_e32 v49, 0xffff0000, v40
	v_pk_fma_f32 v[38:39], v[50:51], v[48:49], v[38:39]
	v_lshlrev_b32_e32 v48, 16, v19
	v_mul_f32_e32 v28, 0xbfb8aa3b, v39
	v_exp_f32_e32 v28, v28
	v_and_b32_e32 v49, 0xffff0000, v19
	v_mul_f32_e32 v16, 0xbfb8aa3b, v46
	v_mul_f32_e32 v18, 0xbfb8aa3b, v38
	v_add_f32_e32 v40, 1.0, v28
	v_pk_fma_f32 v[48:49], v[60:61], v[48:49], 0 op_sel_hi:[1,1,0]
	v_lshlrev_b32_e32 v28, 16, v29
	v_and_b32_e32 v29, 0xffff0000, v29
	v_exp_f32_e32 v16, v16
	v_exp_f32_e32 v18, v18
	v_pk_fma_f32 v[28:29], v[68:69], v[28:29], v[48:49]
	v_lshlrev_b32_e32 v32, 16, v33
	v_and_b32_e32 v33, 0xffff0000, v33
	v_cndmask_b32_e64 v53, 0, v53, s[24:25]
	v_cndmask_b32_e64 v52, 0, v52, s[24:25]
	v_pk_fma_f32 v[28:29], v[76:77], v[32:33], v[28:29]
	v_lshlrev_b32_e32 v32, 16, v41
	v_and_b32_e32 v33, 0xffff0000, v41
	v_pk_fma_f32 v[28:29], v[52:53], v[32:33], v[28:29]
	v_add_f32_e32 v16, 1.0, v16
	v_mul_f32_e32 v19, 0xbfb8aa3b, v28
	v_add_f32_e32 v18, 1.0, v18
	v_exp_f32_e32 v32, v19
	v_mul_f32_e32 v19, 0xbfb8aa3b, v29
	v_rcp_f32_e32 v16, v16
	v_rcp_f32_e32 v18, v18
	v_exp_f32_e32 v33, v19
	v_rcp_f32_e32 v19, v40
	v_add_f32_e32 v30, 1.0, v30
	v_add_f32_e32 v31, 1.0, v31
	v_add_f32_e32 v32, 1.0, v32
	v_add_f32_e32 v33, 1.0, v33
	v_pk_mul_f32 v[132:133], v[46:47], v[16:17]
	v_pk_mul_f32 v[136:137], v[38:39], v[18:19]
	ds_read_b128 v[16:19], v153 offset:544
	v_rcp_f32_e32 v30, v30
	v_rcp_f32_e32 v31, v31
	v_rcp_f32_e32 v32, v32
	v_rcp_f32_e32 v33, v33
	s_waitcnt vmcnt(1)
	v_lshlrev_b32_e32 v54, 16, v12
	v_pk_mul_f32 v[134:135], v[26:27], v[30:31]
	v_cndmask_b32_e64 v31, 0, v37, s[18:19]
	v_pk_mul_f32 v[138:139], v[28:29], v[32:33]
	ds_read_b128 v[26:29], v153 offset:560
	s_waitcnt lgkmcnt(1)
	v_cndmask_b32_e64 v39, 0, v19, s[20:21]
	v_cndmask_b32_e64 v38, 0, v18, s[20:21]
	v_cndmask_b32_e64 v41, 0, v17, s[20:21]
	v_cndmask_b32_e64 v40, 0, v16, s[20:21]
	ds_read_b128 v[16:19], v153 offset:1056
	v_cndmask_b32_e64 v30, 0, v36, s[18:19]
	v_cndmask_b32_e64 v33, 0, v35, s[18:19]
	v_cndmask_b32_e64 v32, 0, v34, s[18:19]
	v_cndmask_b32_e64 v35, 0, v45, s[18:19]
	v_cndmask_b32_e64 v34, 0, v44, s[18:19]
	v_cndmask_b32_e64 v37, 0, v43, s[18:19]
	v_cndmask_b32_e64 v36, 0, v42, s[18:19]
	s_waitcnt lgkmcnt(1)
	v_cndmask_b32_e64 v43, 0, v29, s[20:21]
	v_cndmask_b32_e64 v42, 0, v28, s[20:21]
	v_cndmask_b32_e64 v45, 0, v27, s[20:21]
	v_cndmask_b32_e64 v44, 0, v26, s[20:21]
	ds_read_b128 v[26:29], v153 offset:1072
	s_waitcnt lgkmcnt(1)
	v_cndmask_b32_e64 v47, 0, v19, s[22:23]
	v_cndmask_b32_e64 v46, 0, v18, s[22:23]
	v_cndmask_b32_e64 v49, 0, v17, s[22:23]
	v_cndmask_b32_e64 v48, 0, v16, s[22:23]
	ds_read_b128 v[16:19], v153 offset:1568
	v_and_b32_e32 v55, 0xffff0000, v12
	v_pk_fma_f32 v[32:33], v[32:33], v[54:55], 0 op_sel_hi:[1,1,0]
	v_lshlrev_b32_e32 v54, 16, v0
	v_and_b32_e32 v55, 0xffff0000, v0
	v_pk_fma_f32 v[32:33], v[40:41], v[54:55], v[32:33]
	v_lshlrev_b32_e32 v40, 16, v4
	v_and_b32_e32 v41, 0xffff0000, v4
	s_waitcnt lgkmcnt(1)
	v_cndmask_b32_e64 v51, 0, v29, s[22:23]
	v_cndmask_b32_e64 v50, 0, v28, s[22:23]
	v_cndmask_b32_e64 v53, 0, v27, s[22:23]
	v_cndmask_b32_e64 v52, 0, v26, s[22:23]
	ds_read_b128 v[26:29], v153 offset:1584
	s_waitcnt lgkmcnt(1)
	v_cndmask_b32_e64 v17, 0, v17, s[24:25]
	v_cndmask_b32_e64 v16, 0, v16, s[24:25]
	v_pk_fma_f32 v[32:33], v[48:49], v[40:41], v[32:33]
	s_waitcnt vmcnt(0)
	v_lshlrev_b32_e32 v40, 16, v8
	v_and_b32_e32 v41, 0xffff0000, v8
	v_pk_fma_f32 v[16:17], v[16:17], v[40:41], v[32:33]
	v_lshlrev_b32_e32 v12, 16, v13
	v_mul_f32_e32 v0, 0xbfb8aa3b, v16
	v_exp_f32_e32 v0, v0
	v_mul_f32_e32 v4, 0xbfb8aa3b, v17
	v_exp_f32_e32 v4, v4
	v_and_b32_e32 v13, 0xffff0000, v13
	v_add_f32_e32 v0, 1.0, v0
	v_rcp_f32_e32 v32, v0
	v_pk_fma_f32 v[12:13], v[30:31], v[12:13], 0 op_sel_hi:[1,1,0]
	v_lshlrev_b32_e32 v0, 16, v1
	v_and_b32_e32 v1, 0xffff0000, v1
	v_add_f32_e32 v8, 1.0, v4
	v_pk_fma_f32 v[0:1], v[38:39], v[0:1], v[12:13]
	v_lshlrev_b32_e32 v4, 16, v5
	v_and_b32_e32 v5, 0xffff0000, v5
	v_cndmask_b32_e64 v19, 0, v19, s[24:25]
	v_cndmask_b32_e64 v18, 0, v18, s[24:25]
	v_pk_fma_f32 v[0:1], v[46:47], v[4:5], v[0:1]
	v_lshlrev_b32_e32 v4, 16, v9
	v_and_b32_e32 v5, 0xffff0000, v9
	v_pk_fma_f32 v[18:19], v[18:19], v[4:5], v[0:1]
	v_rcp_f32_e32 v33, v8
	v_mul_f32_e32 v0, 0xbfb8aa3b, v18
	v_exp_f32_e32 v0, v0
	v_mul_f32_e32 v1, 0xbfb8aa3b, v19
	v_exp_f32_e32 v1, v1
	v_lshlrev_b32_e32 v4, 16, v2
	v_add_f32_e32 v0, 1.0, v0
	v_rcp_f32_e32 v30, v0
	v_add_f32_e32 v8, 1.0, v1
	v_lshlrev_b32_e32 v0, 16, v14
	v_and_b32_e32 v1, 0xffff0000, v14
	v_pk_fma_f32 v[0:1], v[36:37], v[0:1], 0 op_sel_hi:[1,1,0]
	v_and_b32_e32 v5, 0xffff0000, v2
	v_pk_fma_f32 v[0:1], v[44:45], v[4:5], v[0:1]
	v_lshlrev_b32_e32 v4, 16, v6
	v_and_b32_e32 v5, 0xffff0000, v6
	s_waitcnt lgkmcnt(0)
; __device__ __forceinline__ float rsq_f(float x) { return __builtin_amdgcn_rsqf(x); }
; __device__ __forceinline__ float red8(float x) { x += dpp_f<0xB1>(x); x += dpp_f<0x4E>(x); x += dpp_f<0x141>(x); return x; }
; __device__ __forceinline__ float* karg_out() { return *(volatile KAS fptr_t*)((const KAS char*)__builtin_amdgcn_kernarg_segment_ptr() + 256); }
; #define lane opq(lane_now())
; __device__ __forceinline__ void delta_prep_wave(const Params& P, LAS unsigned char* lds, int idx, int wave, int lane) {
;     ...
;         float ssk = 0.f, ssq = 0.f;
; #pragma unroll
;         for (int e = 0; e < 16; ++e) { ssk += kv[e] * kv[e]; ssq += qv[e] * qv[e]; }
;         ssk = red8(ssk); ssq = red8(ssq);
;         if ((lane & 7) == 0) { const float nkj = rsq_f(ssk + EPS), nqj = 0.08838834764831845f * rsq_f(ssq + EPS); nks[nloc] = nkj; nqs[nloc] = nqj;
;             ((float*)((unsigned char*)karg_out() + OSB_NK))[(size_t)bh * SEQ + tl] = nkj; ((float*)((unsigned char*)karg_out() + OSB_NQ))[(size_t)bh * SEQ + tl] = nqj; }
	v_cndmask_b32_e64 v27, 0, v27, s[24:25]
	v_cndmask_b32_e64 v26, 0, v26, s[24:25]
	v_pk_fma_f32 v[0:1], v[52:53], v[4:5], v[0:1]
	v_lshlrev_b32_e32 v4, 16, v10
	v_and_b32_e32 v5, 0xffff0000, v10
	v_pk_fma_f32 v[26:27], v[26:27], v[4:5], v[0:1]
	v_lshlrev_b32_e32 v2, 16, v3
	v_mul_f32_e32 v0, 0xbfb8aa3b, v26
	v_exp_f32_e32 v0, v0
	v_mul_f32_e32 v1, 0xbfb8aa3b, v27
	v_exp_f32_e32 v1, v1
	v_and_b32_e32 v3, 0xffff0000, v3
	v_add_f32_e32 v0, 1.0, v0
	v_rcp_f32_e32 v36, v0
	v_add_f32_e32 v37, 1.0, v1
	v_lshlrev_b32_e32 v0, 16, v15
	v_and_b32_e32 v1, 0xffff0000, v15
	v_pk_fma_f32 v[0:1], v[34:35], v[0:1], 0 op_sel_hi:[1,1,0]
	v_cndmask_b32_e64 v29, 0, v29, s[24:25]
	v_pk_fma_f32 v[0:1], v[42:43], v[2:3], v[0:1]
	v_lshlrev_b32_e32 v2, 16, v7
	v_and_b32_e32 v3, 0xffff0000, v7
	v_cndmask_b32_e64 v28, 0, v28, s[24:25]
	v_pk_fma_f32 v[0:1], v[50:51], v[2:3], v[0:1]
	v_lshlrev_b32_e32 v2, 16, v11
	v_and_b32_e32 v3, 0xffff0000, v11
	v_pk_fma_f32 v[28:29], v[28:29], v[2:3], v[0:1]
	v_mul_f32_e32 v0, 0xbfb8aa3b, v28
	v_exp_f32_e32 v34, v0
	v_rcp_f32_e32 v31, v8
	v_mul_f32_e32 v20, 0xbfb8aa3b, v29
	v_exp_f32_e32 v21, v20
	v_add_f32_e32 v20, 1.0, v34
	v_rcp_f32_e32 v37, v37
	v_rcp_f32_e32 v20, v20
	v_add_f32_e32 v21, 1.0, v21
	v_rcp_f32_e32 v21, v21
	v_pk_mul_f32 v[144:145], v[16:17], v[32:33]
	v_pk_mul_f32 v[146:147], v[18:19], v[30:31]
	v_pk_mul_f32 v[148:149], v[26:27], v[36:37]
	v_pk_mul_f32 v[150:151], v[28:29], v[20:21]
	ds_read_b128 v[92:95], v153 offset:4096
	ds_read_b128 v[76:79], v153 offset:4112
	ds_read_b128 v[88:91], v153 offset:4608
	ds_read_b128 v[72:75], v153 offset:4624
	ds_read_b128 v[84:87], v153 offset:5120
	ds_read_b128 v[68:71], v153 offset:5136
	ds_read_b128 v[80:83], v153 offset:5632
	ds_read_b128 v[64:67], v153 offset:5648
	ds_read_b128 v[44:47], v153 offset:4128
	ds_read_b128 v[28:31], v153 offset:4144
	ds_read_b128 v[40:43], v153 offset:4640
	ds_read_b128 v[24:27], v153 offset:4656
	ds_read_b128 v[36:39], v153 offset:5152
	ds_read_b128 v[20:23], v153 offset:5168
	ds_read_b128 v[32:35], v153 offset:5664
	ds_read_b128 v[16:19], v153 offset:5680
	v_pk_mul_f32 v[160:161], v[116:117], v[116:117]
	v_pk_mul_f32 v[162:163], v[132:133], v[132:133]
	v_pk_mul_f32 v[164:165], v[118:119], v[118:119]
	v_pk_mul_f32 v[168:169], v[134:135], v[134:135]
	v_add_f32_e32 v159, v160, v161
	v_add_f32_e32 v160, v162, v163
	v_add_f32_e32 v159, v164, v159
	v_add_f32_e32 v160, v168, v160
	v_pk_mul_f32 v[170:171], v[120:121], v[120:121]
	v_pk_mul_f32 v[172:173], v[136:137], v[136:137]
	v_add_f32_e32 v159, v165, v159
	v_add_f32_e32 v160, v169, v160
	v_add_f32_e32 v159, v170, v159
	v_add_f32_e32 v160, v172, v160
	v_pk_mul_f32 v[174:175], v[122:123], v[122:123]
	v_pk_mul_f32 v[176:177], v[138:139], v[138:139]
	v_add_f32_e32 v159, v171, v159
	v_add_f32_e32 v160, v173, v160
	v_add_f32_e32 v159, v174, v159
	v_add_f32_e32 v160, v176, v160
	v_pk_mul_f32 v[178:179], v[124:125], v[124:125]
	v_pk_mul_f32 v[180:181], v[144:145], v[144:145]
	v_add_f32_e32 v159, v175, v159
	v_add_f32_e32 v160, v177, v160
	v_add_f32_e32 v159, v159, v178
	v_add_f32_e32 v160, v160, v180
	v_pk_mul_f32 v[182:183], v[126:127], v[126:127]
	v_pk_mul_f32 v[184:185], v[146:147], v[146:147]
	v_add_f32_e32 v159, v179, v159
	v_add_f32_e32 v160, v181, v160
	v_add_f32_e32 v159, v182, v159
	v_add_f32_e32 v160, v184, v160
	v_pk_mul_f32 v[186:187], v[128:129], v[128:129]
	v_pk_mul_f32 v[188:189], v[148:149], v[148:149]
	v_add_f32_e32 v159, v183, v159
	v_add_f32_e32 v160, v185, v160
	v_add_f32_e32 v159, v186, v159
	v_add_f32_e32 v160, v188, v160
	v_pk_mul_f32 v[190:191], v[130:131], v[130:131]
	v_pk_mul_f32 v[192:193], v[150:151], v[150:151]
	v_add_f32_e32 v159, v187, v159
	v_add_f32_e32 v160, v189, v160
	v_add_f32_e32 v159, v190, v159
	v_add_f32_e32 v160, v192, v160
	v_add_f32_e32 v159, v191, v159
	v_add_f32_e32 v161, v193, v160
	s_nop 0
	v_add_f32_dpp v159, v159, v159 quad_perm:[1,0,3,2] row_mask:0xf bank_mask:0xf bound_ctrl:1
	v_add_f32_dpp v161, v161, v161 quad_perm:[1,0,3,2] row_mask:0xf bank_mask:0xf bound_ctrl:1
	s_nop 0
	v_add_f32_dpp v159, v159, v159 quad_perm:[2,3,0,1] row_mask:0xf bank_mask:0xf bound_ctrl:1
	v_add_f32_dpp v161, v161, v161 quad_perm:[2,3,0,1] row_mask:0xf bank_mask:0xf bound_ctrl:1
	s_nop 0
	v_mov_b32_dpp v160, v159 row_half_mirror row_mask:0xf bank_mask:0xf bound_ctrl:1
	v_mov_b32_dpp v162, v161 row_half_mirror row_mask:0xf bank_mask:0xf bound_ctrl:1
	s_and_saveexec_b64 s[4:5], s[10:11]
	s_cbranch_execz .LBB0_1038
	v_add_f32_e32 v161, v161, v162
	v_add_f32_e32 v159, v159, v160
	v_add_f32_e32 v160, 0x358637bd, v161
	v_add_f32_e32 v159, 0x358637bd, v159
	v_rsq_f32_e32 v160, v160
	v_rsq_f32_e32 v159, v159
	v_mul_f32_e32 v162, 0x3db504f3, v160
	ds_write2st64_b32 v154, v159, v162 offset1:1
	s_load_dwordx2 s[12:13], s[0:1], 0x100
	s_waitcnt lgkmcnt(0)
	v_lshl_add_u64 v[160:161], s[12:13], 0, v[102:103]
	v_add_co_u32_e32 v160, vcc, 0xfff80000, v160
	s_nop 1
	v_addc_co_u32_e32 v161, vcc, -1, v161, vcc
	global_store_dword v[160:161], v159, off
	s_load_dwordx2 s[12:13], s[0:1], 0x100
	s_waitcnt lgkmcnt(0)
	v_lshl_add_u64 v[160:161], s[12:13], 0, v[102:103]
	global_store_dword v[160:161], v162, off
	s_branch .LBB0_1038
